# P7/P11 K-loop heads at 64-byte alignment, other hot loops at the baseline byte phase (s_nop pads, once per phase), on top of v11
# baseline (speedup 1.0000x reference)
;     __device__ __forceinline__ bool next(int i, Unit& u) const { u.kb = 0; u.nk = 0; return static_tile(i, nM, nN, G, c, u.pm, u.pn); }
; #define PG8_STAGE(bufoff, gbase, voff) do { _Pragma("unroll") for (int _i = 0; _i < 2; ++_i) \
;         __builtin_amdgcn_global_load_lds((const unsigned*)((const char*)(gbase) + (voff)[_i]), (PG8_LAS unsigned*)(lds + (bufoff) + ldsw + _i * 8192), 16, 0, 0); } while (0)
; #define PG8_WAIT_V(n) asm volatile("s_waitcnt vmcnt(" #n ")" ::: "memory")
; #define PG8_BAR __builtin_amdgcn_s_barrier()
; __device__ __forceinline__ bool static_tile(int i, int nM, int nN, int G, int c, int& pm, int& pn) {
;     const int nwg = nM * nN; const long Lx = (long)i * G + c; if (Lx >= nwg) return false;
;     int wgid = (int)Lx; { const int q = nwg / NXCD, r = nwg % NXCD, xcd = wgid % NXCD, off = wgid / NXCD; wgid = (xcd < r ? xcd * (q + 1) : r * (q + 1) + (xcd - r) * q) + off; }
;     const int nig = WGM * nN, gid = wgid / nig, fm = gid * WGM, gsz = (nM - fm) < WGM ? (nM - fm) : WGM;
;     pm = fm + ((wgid % nig) % gsz); pn = (wgid % nig) / gsz; return true;
; template <class Epi, class Sched>
; __device__ __forceinline__ void gemm_phase(PG8_LAS unsigned char* lds, const Gemm g, const Sched& S, const Epi& E) {
;     ...
;     for (int i = 0; i < 2; ++i) { int R, C; stage_rc(tid * 16 + i * 8192, R, C); const int Rb = (R & ~31) + perm32(R & 31);
;         voffA[i] = (unsigned)(R * g.lda + C) * 2u; voffB[i] = (unsigned)(Rb * K + C) * 2u; }
;     const size_t kstep = (size_t)(BK * 2);
;     const size_t hstepA = (size_t)HALF * g.lda * 2, hstepB = (size_t)HALF * K * 2;
;     const unsigned ldsw = (unsigned)wid * 1024u;
;     const int aoff = lds_byte(wr * 64 + fr, fq * 8), boff = lds_byte(wc * 32 + fr, fq * 8);
;     ...
;     Unit cur, nxt; int ui = 0;
;     if (!S.next(0, cur)) return;
;     f32x4 acc[2][2][4][2];
;     E.init(acc, cur, wr, wc, fr, fq);
;     bf16x8 At[4][2], B0[2][2], B1[2][2];
;     const char* cA = PG8_TA(cur); const char* cB = PG8_TB(cur);
;     PG8_STAGE(PG8_SB(0, 0), cB, voffB); PG8_STAGE(PG8_SB(0, 1), cB + hstepB, voffB); PG8_STAGE(PG8_SA(0, 0), cA, voffA); PG8_STAGE(PG8_SA(0, 1), cA + hstepA, voffA);
;     if (wr == 1) PG8_BAR;
;     PG8_WAIT_V(2); PG8_BAR;
;     PG8_STAGE(PG8_SB(1, 0), cB + kstep, voffB); PG8_STAGE(PG8_SA(1, 0), cA + kstep, voffA); PG8_STAGE(PG8_SB(1, 1), cB + hstepB + kstep, voffB);
.LBB0_935:
	s_or_b64 exec, exec, s[0:1]
	s_waitcnt vmcnt(3)
	v_mov_b32_e32 v13, v181
	s_cmpk_lt_i32 s66, 0xb58
	s_waitcnt lgkmcnt(0)
	s_barrier
	s_nop 0
	s_nop 0
	s_nop 0
	s_nop 0
	s_nop 0
	s_nop 0
	s_nop 0
	s_nop 0
	s_nop 0
	s_nop 0
	s_nop 0
	s_nop 0
	s_nop 0
	s_nop 0
	s_movk_i32 s0, 0x400
	v_readfirstlane_b32 s2, v13
	s_cselect_b64 s[24:25], -1, 0
	s_cmpk_gt_i32 s66, 0xb57
	s_cbranch_scc1 .LBB0_954
	s_waitcnt vmcnt(1)
	v_lshlrev_b32_e32 v0, 4, v13
	v_add_u32_e32 v1, 0x2000, v0
	v_ashrrev_i32_e32 v2, 31, v1
	v_lshrrev_b32_e32 v2, 22, v2
	v_add_u32_e32 v2, v1, v2
	v_ashrrev_i32_e32 v12, 10, v2
	v_mul_i32_i24_e32 v2, 0x400, v12
	v_sub_u32_e32 v1, v1, v2
	v_lshrrev_b32_e32 v2, 4, v1
	v_bitop3_b32 v1, v2, v1, 32 bitop3:0x6c
	v_ashrrev_i32_e32 v2, 31, v1
	v_lshrrev_b32_e32 v2, 26, v2
	v_add_u32_e32 v2, v1, v2
	v_lshlrev_b32_e32 v3, 3, v12
	v_ashrrev_i32_e32 v14, 6, v2
	v_and_b32_e32 v3, -16, v3
	v_add_u32_e32 v3, v14, v3
	s_waitcnt vmcnt(0)
	v_and_b32_e32 v4, 3, v14
	s_mov_b32 s4, 0x7fffffe0
	v_lshrrev_b32_e32 v5, 2, v3
	v_lshlrev_b32_e32 v6, 1, v3
	v_and_b32_e32 v2, 0xc0, v2
	v_and_or_b32 v4, v3, s4, v4
	v_and_b32_e32 v5, 4, v5
	v_and_b32_e32 v6, 24, v6
	v_sub_u32_e32 v1, v1, v2
	v_mov_b32_e32 v2, 1
	v_or3_b32 v4, v4, v5, v6
	v_lshlrev_b32_e32 v5, 5, v12
	v_ashrrev_i16_sdwa v1, v2, sext(v1) dst_sel:DWORD dst_unused:UNUSED_PAD src0_sel:DWORD src1_sel:BYTE_0
	v_and_b32_e32 v5, 32, v5
	v_bfe_i32 v15, v1, 0, 16
	v_mul_lo_u32 v4, v4, s0
	v_add_u32_e32 v1, v5, v15
	v_lshlrev_b32_e32 v3, 11, v3
	v_add_lshl_u32 v128, v4, v1, 1
	v_lshl_add_u32 v130, v1, 1, v3
	v_bfe_i32 v1, v13, 27, 1
	v_lshrrev_b32_e32 v1, 22, v1
	v_add_u32_e32 v1, v0, v1
	v_and_b32_e32 v1, 0xfffffc00, v1
	v_sub_u32_e32 v0, v0, v1
	v_lshrrev_b32_e32 v1, 4, v0
	v_ashrrev_i32_e32 v3, 31, v13
	v_bitop3_b32 v0, v1, v0, 32 bitop3:0x6c
	v_lshrrev_b32_e32 v3, 26, v3
	v_ashrrev_i32_e32 v1, 31, v0
	v_add_u32_e32 v3, v13, v3
	v_lshrrev_b32_e32 v1, 26, v1
	v_ashrrev_i32_e32 v17, 6, v3
	v_add_u32_e32 v1, v0, v1
	v_lshlrev_b32_e32 v3, 3, v17
	v_ashrrev_i32_e32 v16, 6, v1
	v_and_b32_e32 v3, -16, v3
	v_add_u32_e32 v3, v16, v3
	v_and_b32_e32 v4, 3, v16
	s_add_u32 s36, s90, 0xc00000
	v_and_or_b32 v4, v3, s4, v4
	v_readlane_b32 s4, v241, 38
	s_addc_u32 s37, s91, 0
	s_lshr_b32 s4, s4, 29
	s_add_i32 s4, s66, s4
	s_ashr_i32 s3, s2, 6
	s_ashr_i32 s1, s0, 31
	s_ashr_i32 s6, s4, 3
	s_and_b32 s4, s4, -8
	s_ashr_i32 s5, s2, 8
	s_lshl_b64 s[14:15], s[0:1], 8
	s_lshl_b32 s38, s3, 10
	s_sub_i32 s4, s66, s4
	s_cmp_lt_i32 s4, 0
	s_movk_i32 s39, 0x16c
	s_cselect_b32 s7, s39, 0x16b
	s_mul_i32 s4, s4, s7
	s_add_i32 s4, s4, s6
	s_mul_hi_i32 s6, s4, 0x2e8ba2e9
	s_lshr_b32 s7, s6, 31
	s_ashr_i32 s6, s6, 5
	v_lshrrev_b32_e32 v5, 2, v3
	v_lshlrev_b32_e32 v6, 1, v3
	v_and_b32_e32 v1, 0xc0, v1
	s_add_i32 s6, s6, s7
	v_and_b32_e32 v5, 4, v5
	v_and_b32_e32 v6, 24, v6
	v_sub_u32_e32 v0, v0, v1
	s_lshl_b32 s8, s6, 3
	v_or3_b32 v4, v4, v5, v6
	v_lshlrev_b32_e32 v5, 5, v17
	v_ashrrev_i16_sdwa v0, v2, sext(v0) dst_sel:DWORD dst_unused:UNUSED_PAD src0_sel:DWORD src1_sel:BYTE_0
	s_sub_i32 s7, 0x84, s8
	s_mulk_i32 s6, 0xb0
	v_and_b32_e32 v5, 32, v5
	v_bfe_i32 v18, v0, 0, 16
	s_min_u32 s9, s7, 8
	s_sub_i32 s10, s4, s6
	v_mul_lo_u32 v4, v4, s0
	v_add_u32_e32 v0, v5, v18
	v_lshlrev_b32_e32 v1, 11, v3
	s_sext_i32_i16 s4, s10
	v_cvt_f32_ubyte0_e32 v3, s9
	v_add_lshl_u32 v132, v4, v0, 1
	v_cvt_f32_i32_e32 v2, s4
	v_rcp_iflag_f32_e32 v4, v3
	v_lshl_add_u32 v134, v0, 1, v1
	s_ashr_i32 s4, s4, 30
	s_or_b32 s4, s4, 1
	v_mul_f32_e32 v0, v2, v4
	v_trunc_f32_e32 v0, v0
	v_fma_f32 v1, -v0, v3, v2
	v_cvt_i32_f32_e32 v0, v0
	v_cmp_ge_f32_e64 s[6:7], |v1|, v3
	s_and_b64 s[6:7], s[6:7], exec
	s_cselect_b32 s4, s4, 0
	v_readfirstlane_b32 s6, v0
	s_add_i32 s4, s6, s4
	s_mul_i32 s6, s4, s9
	s_sub_i32 s6, s10, s6
	s_sext_i32_i16 s6, s6
	s_add_i32 s8, s8, s6
	s_ashr_i32 s9, s8, 31
	s_bfe_i64 s[6:7], s[4:5], 0x100000
	s_lshl_b64 s[16:17], s[0:1], 9
	s_lshl_b64 s[12:13], s[8:9], 19
	s_mul_i32 s7, s16, s7
	s_mul_hi_u32 s9, s16, s6
	s_lshr_b64 s[10:11], s[0:1], 23
	s_add_i32 s7, s9, s7
	s_mul_i32 s9, s10, s6
	s_add_i32 s7, s7, s9
	s_mul_i32 s6, s16, s6
	s_add_u32 s10, s36, s6
	s_addc_u32 s11, s37, s7
	s_add_i32 s40, s38, 0
	s_add_i32 m0, s40, 0x10000
	v_mov_b32_e32 v133, 0
	global_load_lds_dwordx4 v132, s[10:11]
	s_add_i32 m0, s40, 0x12000
	s_add_u32 s6, s10, s14
	global_load_lds_dwordx4 v128, s[10:11]
	s_addc_u32 s7, s11, s15
	s_add_i32 m0, s40, 0x14000
	v_mov_b32_e32 v129, v133
	global_load_lds_dwordx4 v132, s[6:7]
	s_add_i32 m0, s40, 0x16000
	s_add_u32 s12, s86, s12
	s_addc_u32 s13, s87, s13
	s_add_i32 s41, s40, 0x2000
	global_load_lds_dwordx4 v128, s[6:7]
	s_mov_b32 m0, s40
	s_add_u32 s18, s12, 0x40000
	global_load_lds_dwordx4 v134, s[12:13]
	s_mov_b32 m0, s41
	s_addc_u32 s19, s13, 0
	s_add_i32 s42, s40, 0x4000
	global_load_lds_dwordx4 v130, s[12:13]
	s_mov_b32 m0, s42
	s_add_i32 s43, s40, 0x6000
	global_load_lds_dwordx4 v134, s[18:19]
	s_mov_b32 m0, s43
	v_mov_b32_e32 v135, v133
	global_load_lds_dwordx4 v130, s[18:19]
	v_mov_b32_e32 v131, v133
	s_cmp_eq_u32 s5, 1
	s_mov_b32 s44, 0
	v_lshl_add_u64 v[8:9], s[10:11], 0, v[132:133]
	v_lshl_add_u64 v[4:5], s[10:11], 0, v[128:129]
	v_lshl_add_u64 v[2:3], s[6:7], 0, v[132:133]
	v_lshl_add_u64 v[0:1], s[6:7], 0, v[128:129]
	v_lshl_add_u64 v[6:7], s[12:13], 0, v[134:135]
	s_cselect_b64 s[18:19], -1, 0
	s_cmp_lg_u32 s5, 1
	v_lshl_add_u64 v[10:11], s[12:13], 0, v[130:131]
	s_cbranch_scc1 .LBB0_938
	s_barrier

;     __device__ __forceinline__ void init(f32x4 (&acc)[2][2][4][2], const Unit&, int, int, int, int) const { acc_zero(acc); }
;     __device__ __forceinline__ void init(f32x4 (&acc)[2][2][4][2], const Unit&, int, int, int, int) const { acc_zero(acc); }
;     __device__ __forceinline__ void init(f32x4 (&acc)[2][2][4][2], const Unit&, int, int, int, int) const { acc_zero(acc); }
; __global__ void __launch_bounds__(512, 2) fwd_kernel(Args a) {
;     ...
;     { pg8::Gemm g{H, WD, M, D, FF, FF, 0}; pg8::TailOrder ST; ST.init(FF, G, bx); EpiRes<false, true> E{nullptr, nullptr, XB, SSQ + M, PART}; pg8::gemm_phase(L, g, ST, E); }
.LBB0_1014:
	s_or_b64 exec, exec, s[0:1]
	s_cmpk_lt_i32 s66, 0x200
	s_cselect_b64 s[0:1], -1, 0
	s_cmpk_gt_i32 s66, 0x1ff
	s_mov_b32 s42, 0
	s_waitcnt lgkmcnt(0)
	s_barrier
	s_nop 0
	s_nop 0
	s_nop 0
	s_nop 0
	s_nop 0
	s_nop 0
	s_nop 0
	s_cbranch_scc1 .LBB0_1016
	s_sub_i32 s2, s92, s66
	s_add_i32 s3, s2, 0x1ff
	s_sub_i32 s2, 0xfffffe01, s2
	s_max_i32 s2, s3, s2
	s_ashr_i32 s4, s3, 31
	v_readlane_b32 s5, v241, 37
	s_mul_hi_u32 s3, s2, s76
	s_xor_b32 s4, s4, s5
	s_mul_i32 s5, s3, s69
	s_sub_i32 s2, s2, s5
	s_add_i32 s5, s3, 1
	s_sub_i32 s6, s2, s69
	s_cmp_ge_u32 s2, s69
	s_cselect_b32 s3, s5, s3
	s_cselect_b32 s2, s6, s2
	s_add_i32 s5, s3, 1
	s_cmp_ge_u32 s2, s69
	s_cselect_b32 s2, s5, s3
	s_xor_b32 s2, s2, s4
	s_sub_i32 s42, s2, s4

;     __device__ __forceinline__ bool next(int i, Unit& u) const { u.kb = 0; u.nk = 0; return static_tile(i, nM, nN, G, c, u.pm, u.pn); }
; #define PG8_STAGE(bufoff, gbase, voff) do { _Pragma("unroll") for (int _i = 0; _i < 2; ++_i) \
;         __builtin_amdgcn_global_load_lds((const unsigned*)((const char*)(gbase) + (voff)[_i]), (PG8_LAS unsigned*)(lds + (bufoff) + ldsw + _i * 8192), 16, 0, 0); } while (0)
; #define PG8_BAR __builtin_amdgcn_s_barrier()
; __device__ __forceinline__ bool static_tile(int i, int nM, int nN, int G, int c, int& pm, int& pn) {
;     const int nwg = nM * nN; const long Lx = (long)i * G + c; if (Lx >= nwg) return false;
;     int wgid = (int)Lx; { const int q = nwg / NXCD, r = nwg % NXCD, xcd = wgid % NXCD, off = wgid / NXCD; wgid = (xcd < r ? xcd * (q + 1) : r * (q + 1) + (xcd - r) * q) + off; }
;     const int nig = WGM * nN, gid = wgid / nig, fm = gid * WGM, gsz = (nM - fm) < WGM ? (nM - fm) : WGM;
;     pm = fm + ((wgid % nig) % gsz); pn = (wgid % nig) / gsz; return true;
; template <class Epi, class Sched>
; __device__ __forceinline__ void gemm_phase(PG8_LAS unsigned char* lds, const Gemm g, const Sched& S, const Epi& E) {
;     ...
;     const int wid = __builtin_amdgcn_readfirstlane(tid >> 6), lane = tid & 63, wr = wid >> 2, wc = wid & 3, fr = lane & 15, fq = lane >> 4;
;     int K = g.K; asm volatile("" : "+s"(K));
;     const int ntfull = K / BK;
;     unsigned voffA[2], voffB[2];
; #pragma unroll
;     for (int i = 0; i < 2; ++i) { int R, C; stage_rc(tid * 16 + i * 8192, R, C); const int Rb = (R & ~31) + perm32(R & 31);
;         voffA[i] = (unsigned)(R * g.lda + C) * 2u; voffB[i] = (unsigned)(Rb * K + C) * 2u; }
;     const size_t kstep = (size_t)(BK * 2);
;     const size_t hstepA = (size_t)HALF * g.lda * 2, hstepB = (size_t)HALF * K * 2;
;     const unsigned ldsw = (unsigned)wid * 1024u;
;     const int aoff = lds_byte(wr * 64 + fr, fq * 8), boff = lds_byte(wc * 32 + fr, fq * 8);
;     ...
;     Unit cur, nxt; int ui = 0;
;     if (!S.next(0, cur)) return;
;     f32x4 acc[2][2][4][2];
;     E.init(acc, cur, wr, wc, fr, fq);
;     bf16x8 At[4][2], B0[2][2], B1[2][2];
;     const char* cA = PG8_TA(cur); const char* cB = PG8_TB(cur);
;     PG8_STAGE(PG8_SB(0, 0), cB, voffB); PG8_STAGE(PG8_SB(0, 1), cB + hstepB, voffB); PG8_STAGE(PG8_SA(0, 0), cA, voffA); PG8_STAGE(PG8_SA(0, 1), cA + hstepA, voffA);
;     if (wr == 1) PG8_BAR;
.LBB0_1589:
	s_or_b64 exec, exec, s[0:1]
	v_mov_b32_e32 v13, v181
	s_waitcnt lgkmcnt(0)
	s_barrier
	s_nop 0
	s_nop 0
	s_nop 0
	s_nop 0
	s_nop 0
	s_nop 0
	s_nop 0
	s_movk_i32 s0, 0x400
	v_readfirstlane_b32 s3, v13
	s_andn2_b64 vcc, exec, s[24:25]
	s_cbranch_vccnz .LBB0_1608
	v_lshlrev_b32_e32 v0, 4, v13
	v_add_u32_e32 v1, 0x2000, v0
	v_ashrrev_i32_e32 v2, 31, v1
	v_lshrrev_b32_e32 v2, 22, v2
	v_add_u32_e32 v2, v1, v2
	v_ashrrev_i32_e32 v12, 10, v2
	v_mul_i32_i24_e32 v2, 0x400, v12
	v_sub_u32_e32 v1, v1, v2
	v_lshrrev_b32_e32 v2, 4, v1
	v_bitop3_b32 v1, v2, v1, 32 bitop3:0x6c
	v_ashrrev_i32_e32 v2, 31, v1
	v_lshrrev_b32_e32 v2, 26, v2
	v_add_u32_e32 v2, v1, v2
	v_lshlrev_b32_e32 v3, 3, v12
	v_ashrrev_i32_e32 v14, 6, v2
	v_and_b32_e32 v3, -16, v3
	v_add_u32_e32 v3, v14, v3
	v_and_b32_e32 v4, 3, v14
	s_mov_b32 s2, 0x7fffffe0
	v_lshrrev_b32_e32 v5, 2, v3
	v_lshlrev_b32_e32 v6, 1, v3
	v_and_b32_e32 v2, 0xc0, v2
	v_and_or_b32 v4, v3, s2, v4
	v_and_b32_e32 v5, 4, v5
	v_and_b32_e32 v6, 24, v6
	v_sub_u32_e32 v1, v1, v2
	v_mov_b32_e32 v2, 1
	v_or3_b32 v4, v4, v5, v6
	v_lshlrev_b32_e32 v5, 5, v12
	v_ashrrev_i16_sdwa v1, v2, sext(v1) dst_sel:DWORD dst_unused:UNUSED_PAD src0_sel:DWORD src1_sel:BYTE_0
	v_and_b32_e32 v5, 32, v5
	v_bfe_i32 v15, v1, 0, 16
	v_mul_lo_u32 v4, v4, s0
	v_add_u32_e32 v1, v5, v15
	v_lshlrev_b32_e32 v3, 11, v3
	v_add_lshl_u32 v128, v4, v1, 1
	v_lshl_add_u32 v132, v1, 1, v3
	v_bfe_i32 v1, v13, 27, 1
	v_lshrrev_b32_e32 v1, 22, v1
	v_add_u32_e32 v1, v0, v1
	v_and_b32_e32 v1, 0xfffffc00, v1
	v_sub_u32_e32 v0, v0, v1
	v_lshrrev_b32_e32 v1, 4, v0
	v_ashrrev_i32_e32 v3, 31, v13
	v_bitop3_b32 v0, v1, v0, 32 bitop3:0x6c
	v_lshrrev_b32_e32 v3, 26, v3
	v_ashrrev_i32_e32 v1, 31, v0
	v_add_u32_e32 v3, v13, v3
	v_lshrrev_b32_e32 v1, 26, v1
	v_ashrrev_i32_e32 v17, 6, v3
	v_add_u32_e32 v1, v0, v1
	v_lshlrev_b32_e32 v3, 3, v17
	v_ashrrev_i32_e32 v16, 6, v1
	v_and_b32_e32 v3, -16, v3
	v_add_u32_e32 v3, v16, v3
	v_and_b32_e32 v4, 3, v16
	s_add_u32 s36, s90, 0x1700000
	v_and_or_b32 v4, v3, s2, v4
	v_readlane_b32 s2, v241, 38
	s_addc_u32 s37, s91, 0
	s_lshr_b32 s2, s2, 29
	s_add_i32 s2, s64, s2
	s_ashr_i32 s6, s3, 6
	s_ashr_i32 s1, s0, 31
	s_ashr_i32 s8, s2, 3
	s_and_b32 s2, s2, -8
	s_ashr_i32 s7, s3, 8
	s_lshl_b64 s[16:17], s[0:1], 8
	s_lshl_b32 s38, s6, 10
	s_sub_i32 s2, s64, s2
	s_cmp_lt_i32 s2, 0
	s_movk_i32 s39, 0x16c
	s_cselect_b32 s9, s39, 0x16b
	s_mul_i32 s2, s2, s9
	s_add_i32 s2, s2, s8
	s_mul_hi_i32 s8, s2, 0x2e8ba2e9
	s_lshr_b32 s9, s8, 31
	s_ashr_i32 s8, s8, 5
	v_lshrrev_b32_e32 v5, 2, v3
	v_lshlrev_b32_e32 v6, 1, v3
	v_and_b32_e32 v1, 0xc0, v1
	s_add_i32 s8, s8, s9
	v_and_b32_e32 v5, 4, v5
	v_and_b32_e32 v6, 24, v6
	v_sub_u32_e32 v0, v0, v1
	s_lshl_b32 s10, s8, 3
	v_or3_b32 v4, v4, v5, v6
	v_lshlrev_b32_e32 v5, 5, v17
	v_ashrrev_i16_sdwa v0, v2, sext(v0) dst_sel:DWORD dst_unused:UNUSED_PAD src0_sel:DWORD src1_sel:BYTE_0
	s_sub_i32 s9, 0x84, s10
	s_mulk_i32 s8, 0xb0
	v_and_b32_e32 v5, 32, v5
	v_bfe_i32 v18, v0, 0, 16
	s_min_u32 s11, s9, 8
	s_sub_i32 s12, s2, s8
	v_mul_lo_u32 v4, v4, s0
	v_add_u32_e32 v0, v5, v18
	v_lshlrev_b32_e32 v1, 11, v3
	s_sext_i32_i16 s2, s12
	v_cvt_f32_ubyte0_e32 v3, s11
	v_add_lshl_u32 v134, v4, v0, 1
	v_cvt_f32_i32_e32 v2, s2
	v_rcp_iflag_f32_e32 v4, v3
	v_lshl_add_u32 v136, v0, 1, v1
	s_ashr_i32 s2, s2, 30
	s_or_b32 s2, s2, 1
	v_mul_f32_e32 v0, v2, v4
	v_trunc_f32_e32 v0, v0
	v_fma_f32 v1, -v0, v3, v2
	v_cvt_i32_f32_e32 v0, v0
	v_cmp_ge_f32_e64 s[8:9], |v1|, v3
	s_and_b64 s[8:9], s[8:9], exec
	s_cselect_b32 s2, s2, 0
	v_readfirstlane_b32 s8, v0
	s_add_i32 s2, s8, s2
	s_mul_i32 s8, s2, s11
	s_sub_i32 s8, s12, s8
	s_sext_i32_i16 s8, s8
	s_add_i32 s8, s10, s8
	s_ashr_i32 s9, s8, 31
	s_bfe_i64 s[10:11], s[2:3], 0x100000
	s_lshl_b64 s[18:19], s[0:1], 9
	s_lshl_b64 s[12:13], s[8:9], 19
	s_mul_i32 s9, s18, s11
	s_mul_hi_u32 s11, s18, s10
	s_lshr_b64 s[20:21], s[0:1], 23
	s_add_i32 s9, s11, s9
	s_mul_i32 s11, s20, s10
	s_add_i32 s9, s9, s11
	s_mul_i32 s10, s18, s10
	s_add_u32 s10, s36, s10
	s_addc_u32 s11, s37, s9
	s_add_i32 s40, s38, 0
	s_add_i32 m0, s40, 0x10000
	v_mov_b32_e32 v135, 0
	global_load_lds_dwordx4 v134, s[10:11]
	s_add_i32 m0, s40, 0x12000
	s_add_u32 s20, s10, s16
	global_load_lds_dwordx4 v128, s[10:11]
	s_addc_u32 s21, s11, s17
	s_add_i32 m0, s40, 0x14000
	v_mov_b32_e32 v129, v135
	global_load_lds_dwordx4 v134, s[20:21]
	s_add_i32 m0, s40, 0x16000
	s_add_u32 s12, s86, s12
	s_addc_u32 s13, s87, s13
	s_add_i32 s41, s40, 0x2000
	global_load_lds_dwordx4 v128, s[20:21]
	s_mov_b32 m0, s40
	s_add_u32 s24, s12, 0x40000
	global_load_lds_dwordx4 v136, s[12:13]
	s_mov_b32 m0, s41
	s_addc_u32 s25, s13, 0
	s_add_i32 s42, s40, 0x4000
	global_load_lds_dwordx4 v132, s[12:13]
	s_mov_b32 m0, s42
	s_add_i32 s43, s40, 0x6000
	global_load_lds_dwordx4 v136, s[24:25]
	s_mov_b32 m0, s43
	v_mov_b32_e32 v137, v135
	global_load_lds_dwordx4 v132, s[24:25]
	v_mov_b32_e32 v133, v135
	s_cmp_eq_u32 s7, 1
	s_mov_b32 s44, 0
	v_lshl_add_u64 v[8:9], s[10:11], 0, v[134:135]
	v_lshl_add_u64 v[4:5], s[10:11], 0, v[128:129]
	v_lshl_add_u64 v[2:3], s[20:21], 0, v[134:135]
	v_lshl_add_u64 v[0:1], s[20:21], 0, v[128:129]
	v_lshl_add_u64 v[6:7], s[12:13], 0, v[136:137]
	s_cselect_b64 s[20:21], -1, 0
	s_cmp_lg_u32 s7, 1
	v_lshl_add_u64 v[10:11], s[12:13], 0, v[132:133]
	s_cbranch_scc1 .LBB0_1592
	s_barrier

;     __device__ __forceinline__ void init(f32x4 (&acc)[2][2][4][2], const Unit&, int, int, int, int) const { acc_zero(acc); }
;     __device__ __forceinline__ void init(f32x4 (&acc)[2][2][4][2], const Unit&, int, int, int, int) const { acc_zero(acc); }
;     __device__ __forceinline__ void init(f32x4 (&acc)[2][2][4][2], const Unit&, int, int, int, int) const { acc_zero(acc); }
; __global__ void __launch_bounds__(512, 2) fwd_kernel(Args a) {
;     ...
;     { pg8::Gemm g{H, WD + (size_t)D * FF, M, D, FF, FF, 0}; pg8::TailOrder ST; ST.init(FF, G, bx); EpiRes<false, true> E{nullptr, nullptr, XB, SSQ + 3 * M, PART}; pg8::gemm_phase(L, g, ST, E); }
.LBB0_1660:
	s_or_b64 exec, exec, s[0:1]
	s_and_b64 vcc, exec, s[4:5]
	s_mov_b32 s34, 0
	s_waitcnt lgkmcnt(0)
	s_barrier
	s_nop 0
	s_nop 0
	s_nop 0
	s_nop 0
	s_nop 0
	s_nop 0
	s_nop 0
	s_cbranch_vccnz .LBB0_1662
	s_sub_i32 s0, s92, s64
	s_add_i32 s1, s0, 0x1ff
	s_sub_i32 s0, 0xfffffe01, s0
	s_max_i32 s0, s1, s0
	s_ashr_i32 s2, s1, 31
	v_readlane_b32 s3, v241, 37
	s_mul_hi_u32 s1, s0, s76
	s_xor_b32 s2, s2, s3
	s_mul_i32 s3, s1, s69
	s_sub_i32 s0, s0, s3
	s_add_i32 s3, s1, 1
	s_sub_i32 s6, s0, s69
	s_cmp_ge_u32 s0, s69
	s_cselect_b32 s1, s3, s1
	s_cselect_b32 s0, s6, s0
	s_add_i32 s3, s1, 1
	s_cmp_ge_u32 s0, s69
	s_cselect_b32 s0, s3, s1
	s_xor_b32 s0, s0, s2
	s_sub_i32 s34, s0, s2
